# MIX-2 queue reordered; blocks >= 256 enter the MIX-2 queue ~10us later (spin) so the long items land one per CU
# speedup vs baseline: 1.0410x; 1.0410x over previous
.LBB0_524:
	s_or_b64 exec, exec, s[2:3]
	s_barrier
	v_readlane_b32 s4, v255, 14
	s_nop 1
	s_cmp_lt_u32 s4, 256
	s_cbranch_scc1 .LBB0_529
	s_movk_i32 s4, 1500
.Lmx_dly:
	s_nop 15
	s_sub_u32 s4, s4, 1
	s_cmp_lg_u32 s4, 0
	s_cbranch_scc1 .Lmx_dly
	s_branch .LBB0_529
